# grid barrier, XCD leader: no wait for the cross-XCD release atomic's acknowledgement before the leader's own acquire invalidate and local release (waits moved to first consumer; the final vmcnt(0) sti
# baseline (speedup 1.0000x reference)
.LBB0_122:
	s_or_b64 exec, exec, s[4:5]
	s_mov_b64 s[4:5], exec
	v_mbcnt_lo_u32_b32 v0, s4, 0
	v_mbcnt_hi_u32_b32 v0, s5, v0
	v_cmp_eq_u32_e32 vcc, 0, v0
	buffer_inv sc1
	s_and_saveexec_b64 s[8:9], vcc
	s_cbranch_execz .LBB0_124
	s_bcnt1_i32_b64 s4, s[4:5]
	v_mov_b32_e32 v0, 0x2000
	v_mov_b32_e32 v1, s4
	global_atomic_add v0, v1, s[0:1] offset:1024

.LBB0_368:
	s_or_b64 exec, exec, s[6:7]
	s_mov_b64 s[6:7], exec
	v_mbcnt_lo_u32_b32 v0, s6, 0
	v_mbcnt_hi_u32_b32 v0, s7, v0
	v_cmp_eq_u32_e32 vcc, 0, v0
	buffer_inv sc1
	s_and_saveexec_b64 s[8:9], vcc
	s_cbranch_execz .LBB0_370
	s_bcnt1_i32_b64 s6, s[6:7]
	v_mov_b32_e32 v0, 0x2000
	v_mov_b32_e32 v1, s6
	global_atomic_add v0, v1, s[4:5] offset:1024

.LBB0_617:
	s_or_b64 exec, exec, s[8:9]
	s_mov_b64 s[8:9], exec
	v_mbcnt_lo_u32_b32 v0, s8, 0
	v_mbcnt_hi_u32_b32 v0, s9, v0
	v_cmp_eq_u32_e32 vcc, 0, v0
	buffer_inv sc1
	s_and_saveexec_b64 s[12:13], vcc
	s_cbranch_execz .LBB0_619
	s_bcnt1_i32_b64 s8, s[8:9]
	v_mov_b32_e32 v0, 0x2000
	v_mov_b32_e32 v1, s8
	global_atomic_add v0, v1, s[4:5] offset:1024

.LBB0_715:
	s_or_b64 exec, exec, s[8:9]
	s_mov_b64 s[8:9], exec
	v_mbcnt_lo_u32_b32 v0, s8, 0
	v_mbcnt_hi_u32_b32 v0, s9, v0
	v_cmp_eq_u32_e32 vcc, 0, v0
	buffer_inv sc1
	s_and_saveexec_b64 s[16:17], vcc
	s_cbranch_execz .LBB0_717
	s_bcnt1_i32_b64 s8, s[8:9]
	v_mov_b32_e32 v0, 0x2000
	v_mov_b32_e32 v1, s8
	global_atomic_add v0, v1, s[4:5] offset:1024

.LBB0_1112:
	s_or_b64 exec, exec, s[4:5]
	s_mov_b64 s[4:5], exec
	v_mbcnt_lo_u32_b32 v0, s4, 0
	v_mbcnt_hi_u32_b32 v0, s5, v0
	v_cmp_eq_u32_e32 vcc, 0, v0
	buffer_inv sc1
	s_and_saveexec_b64 s[6:7], vcc
	s_cbranch_execz .LBB0_1114
	s_bcnt1_i32_b64 s4, s[4:5]
	v_mov_b32_e32 v0, 0x2000
	v_mov_b32_e32 v1, s4
	global_atomic_add v0, v1, s[2:3] offset:1024
